# GEMM K-loops: 8 of the 16 LDS-DMA loads per iteration use the SGPR-base address form (their 64-bit VALU address adds deleted: four load segments now VALU-free), on top of the static wave priority
# speedup vs baseline: 1.0121x; 1.0121x over previous
; #define PG8_STAGE(bufoff, gbase, voff) do { _Pragma("unroll") for (int _i = 0; _i < 2; ++_i) \
;         __builtin_amdgcn_global_load_lds((const unsigned*)((const char*)(gbase) + (voff)[_i]), (LAS unsigned*)(lds + (bufoff) + ldsw + _i * 8192), 16, 0, 0); } while (0)
; #define PG8_LDA(dst, b, h) do { _Pragma("unroll") for (int m = 0; m < 4; ++m) _Pragma("unroll") for (int k = 0; k < 2; ++k) dst[m][k] = *(const LAS bf16x8*)(lds + PG8_SA(b, h) + aoff + m * 2048 + k * 1024); } while (0)
; #define PG8_LDB(dst, b, h) do { _Pragma("unroll") for (int n = 0; n < 2; ++n) _Pragma("unroll") for (int k = 0; k < 2; ++k) dst[n][k] = *(const LAS bf16x8*)(lds + PG8_SB(b, h) + boff + n * 2048 + k * 1024); } while (0)
; #define PG8_MMA(ai, bj, At, Bt) do { __builtin_amdgcn_s_setprio(1); _Pragma("unroll") for (int m = 0; m < 4; ++m) _Pragma("unroll") for (int n = 0; n < 2; ++n) _Pragma("unroll") for (int k = 0; k < 2; ++k) \
;         acc[ai][bj][m][n] = __builtin_amdgcn_mfma_f32_16x16x32_bf16(Bt[n][k], At[m][k], acc[ai][bj][m][n], 0, 0, 0); __builtin_amdgcn_s_setprio(0); } while (0)
; #define PG8_WAIT_V(n) asm volatile("s_waitcnt vmcnt(" #n ")" ::: "memory")
; #define PG8_WAIT_L(n) asm volatile("s_waitcnt lgkmcnt(" #n ")" ::: "memory")
; #define PG8_BAR __builtin_amdgcn_s_barrier()
; #define PG8_SCHED __builtin_amdgcn_sched_barrier(0)
; template <class Epi>
; __device__ __forceinline__ void gemm_phase(LAS unsigned char* lds, const Gemm g, const StaticOrder& S, const Epi& E) {
;     ...
;             PG8_LDB(B0, 0, 0); PG8_SCHED; PG8_LDA(At, 0, 0); PG8_STAGE(PG8_SA(1, 1), a1 + hstep, voffA);
;             PG8_WAIT_L(8); PG8_BAR; PG8_WAIT_L(0); PG8_MMA(0, 0, At, B0); PG8_BAR; PG8_SCHED;
;             PG8_LDB(B1, 0, 1); PG8_STAGE(PG8_SB(0, 0), b2, voffB);
;             PG8_BAR; PG8_WAIT_L(0); PG8_MMA(0, 1, At, B1); PG8_BAR;
;             PG8_LDA(At, 0, 1); PG8_STAGE(PG8_SA(0, 0), a2, voffA);
;             PG8_BAR; PG8_WAIT_L(0); PG8_MMA(1, 0, At, B0); PG8_BAR; PG8_SCHED;
;             PG8_STAGE(PG8_SB(0, 1), b2 + hstep, voffB);
;             PG8_WAIT_V(6); PG8_BAR; PG8_MMA(1, 1, At, B1); PG8_BAR;
.LBB0_80:
	ds_read_b128 v[154:157], v173
	ds_read_b128 v[176:179], v173 offset:1024
	ds_read_b128 v[180:183], v173 offset:2048
	ds_read_b128 v[184:187], v173 offset:3072
	s_add_u32 s26, s12, 0xfff80080
	s_addc_u32 s27, s13, -1
	s_cmp_eq_u32 s67, 28
	s_cselect_b32 s29, s7, s27
	s_cselect_b32 s28, s63, s26
	s_cselect_b32 s27, s25, s66
	s_cselect_b32 s26, s64, s65
	s_add_i32 m0, s42, 0xc000
	ds_read_b128 v[188:191], v174
	ds_read_b128 v[192:195], v174 offset:1024
	ds_read_b128 v[196:199], v174 offset:2048
	ds_read_b128 v[200:203], v174 offset:3072
	ds_read_b128 v[204:207], v174 offset:4096
	ds_read_b128 v[208:211], v174 offset:5120
	ds_read_b128 v[212:215], v174 offset:6144
	ds_read_b128 v[216:219], v174 offset:7168
	global_load_lds_dwordx4 v146, s[12:13]
	s_add_i32 m0, s42, 0xe000
	s_nop 0
	global_load_lds_dwordx4 v148, s[12:13]
	s_waitcnt lgkmcnt(8)
	s_barrier
	s_waitcnt lgkmcnt(0)
	s_waitcnt lgkmcnt(0)
	v_mfma_f32_16x16x32_bf16 v[124:127], v[154:157], v[188:191], v[124:127]
	v_mfma_f32_16x16x32_bf16 v[120:123], v[180:183], v[188:191], v[120:123]
	v_mfma_f32_16x16x32_bf16 v[116:119], v[154:157], v[196:199], v[116:119]
	v_mfma_f32_16x16x32_bf16 v[112:115], v[180:183], v[196:199], v[112:115]
	v_mfma_f32_16x16x32_bf16 v[100:103], v[154:157], v[204:207], v[100:103]
	v_mfma_f32_16x16x32_bf16 v[96:99], v[180:183], v[204:207], v[96:99]
	v_mfma_f32_16x16x32_bf16 v[76:79], v[154:157], v[212:215], v[76:79]
	v_mfma_f32_16x16x32_bf16 v[72:75], v[180:183], v[212:215], v[72:75]
	v_mfma_f32_16x16x32_bf16 v[124:127], v[176:179], v[192:195], v[124:127]
	v_mfma_f32_16x16x32_bf16 v[120:123], v[184:187], v[192:195], v[120:123]
	v_mfma_f32_16x16x32_bf16 v[116:119], v[176:179], v[200:203], v[116:119]
	v_mfma_f32_16x16x32_bf16 v[112:115], v[184:187], v[200:203], v[112:115]
	v_mfma_f32_16x16x32_bf16 v[100:103], v[176:179], v[208:211], v[100:103]
	v_mfma_f32_16x16x32_bf16 v[96:99], v[184:187], v[208:211], v[96:99]
	v_mfma_f32_16x16x32_bf16 v[76:79], v[176:179], v[216:219], v[76:79]
	v_mfma_f32_16x16x32_bf16 v[72:75], v[184:187], v[216:219], v[72:75]
	s_barrier
	s_add_i32 s68, s55, s35
	v_lshl_add_u64 v[236:237], s[26:27], 0, v[140:141]
	s_mov_b32 m0, s68
	ds_read_b128 v[220:223], v175
	ds_read_b128 v[224:227], v175 offset:1024
	ds_read_b128 v[228:231], v175 offset:2048
	ds_read_b128 v[232:235], v175 offset:3072
	global_load_lds_dwordx4 v[236:237], off
	v_lshl_add_u64 v[238:239], s[26:27], 0, v[136:137]
	s_add_i32 m0, s68, 0x2000
	s_nop 0
	global_load_lds_dwordx4 v[238:239], off
	s_barrier
	s_waitcnt lgkmcnt(0)
	s_waitcnt lgkmcnt(0)
	v_mfma_f32_16x16x32_bf16 v[108:111], v[220:223], v[188:191], v[108:111]
	v_mfma_f32_16x16x32_bf16 v[104:107], v[228:231], v[188:191], v[104:107]
	v_mfma_f32_16x16x32_bf16 v[92:95], v[220:223], v[196:199], v[92:95]
	v_mfma_f32_16x16x32_bf16 v[88:91], v[228:231], v[196:199], v[88:91]
	v_mfma_f32_16x16x32_bf16 v[84:87], v[220:223], v[204:207], v[84:87]
	v_mfma_f32_16x16x32_bf16 v[80:83], v[228:231], v[204:207], v[80:83]
	v_mfma_f32_16x16x32_bf16 v[68:71], v[220:223], v[212:215], v[68:71]
	v_mfma_f32_16x16x32_bf16 v[64:67], v[228:231], v[212:215], v[64:67]
	v_mfma_f32_16x16x32_bf16 v[108:111], v[224:227], v[192:195], v[108:111]
	v_mfma_f32_16x16x32_bf16 v[104:107], v[232:235], v[192:195], v[104:107]
	v_mfma_f32_16x16x32_bf16 v[92:95], v[224:227], v[200:203], v[92:95]
	v_mfma_f32_16x16x32_bf16 v[88:91], v[232:235], v[200:203], v[88:91]
	v_mfma_f32_16x16x32_bf16 v[84:87], v[224:227], v[208:211], v[84:87]
	v_mfma_f32_16x16x32_bf16 v[80:83], v[232:235], v[208:211], v[80:83]
	v_mfma_f32_16x16x32_bf16 v[68:71], v[224:227], v[216:219], v[68:71]
	v_mfma_f32_16x16x32_bf16 v[64:67], v[232:235], v[216:219], v[64:67]
	s_mov_b32 m0, s42
	v_lshl_add_u64 v[240:241], s[28:29], 0, v[142:143]
	s_barrier
	ds_read_b128 v[188:191], v174 offset:16384
	ds_read_b128 v[192:195], v174 offset:17408
	ds_read_b128 v[196:199], v174 offset:18432
	ds_read_b128 v[200:203], v174 offset:19456
	ds_read_b128 v[204:207], v174 offset:20480
	ds_read_b128 v[208:211], v174 offset:21504
	ds_read_b128 v[212:215], v174 offset:22528
	ds_read_b128 v[216:219], v174 offset:23552
	global_load_lds_dwordx4 v[240:241], off
	v_lshl_add_u64 v[242:243], s[28:29], 0, v[138:139]
	s_mov_b32 m0, s43
	s_nop 0
	global_load_lds_dwordx4 v[242:243], off
	s_barrier
	s_waitcnt lgkmcnt(0)
	s_waitcnt lgkmcnt(0)
	v_mfma_f32_16x16x32_bf16 v[60:63], v[154:157], v[188:191], v[60:63]
	v_mfma_f32_16x16x32_bf16 v[56:59], v[180:183], v[188:191], v[56:59]
	v_mfma_f32_16x16x32_bf16 v[52:55], v[154:157], v[196:199], v[52:55]
	v_mfma_f32_16x16x32_bf16 v[48:51], v[180:183], v[196:199], v[48:51]
	v_mfma_f32_16x16x32_bf16 v[36:39], v[154:157], v[204:207], v[36:39]
	v_mfma_f32_16x16x32_bf16 v[32:35], v[180:183], v[204:207], v[32:35]
	v_mfma_f32_16x16x32_bf16 v[12:15], v[154:157], v[212:215], v[12:15]
	v_mfma_f32_16x16x32_bf16 v[8:11], v[180:183], v[212:215], v[8:11]
	v_mfma_f32_16x16x32_bf16 v[60:63], v[176:179], v[192:195], v[60:63]
	v_mfma_f32_16x16x32_bf16 v[56:59], v[184:187], v[192:195], v[56:59]
	v_mfma_f32_16x16x32_bf16 v[52:55], v[176:179], v[200:203], v[52:55]
	v_mfma_f32_16x16x32_bf16 v[48:51], v[184:187], v[200:203], v[48:51]
	v_mfma_f32_16x16x32_bf16 v[36:39], v[176:179], v[208:211], v[36:39]
	v_mfma_f32_16x16x32_bf16 v[32:35], v[184:187], v[208:211], v[32:35]
	v_mfma_f32_16x16x32_bf16 v[12:15], v[176:179], v[216:219], v[12:15]
	v_mfma_f32_16x16x32_bf16 v[8:11], v[184:187], v[216:219], v[8:11]
	s_barrier
	s_add_u32 s68, s26, 0x80000
	s_addc_u32 s69, s27, 0
	s_add_i32 s70, s56, s35
	s_mov_b32 m0, s70
	s_nop 0
	global_load_lds_dwordx4 v140, s[68:69]
	s_add_i32 m0, s70, 0x2000
	s_nop 0
	global_load_lds_dwordx4 v136, s[68:69]
	s_waitcnt vmcnt(6)
	s_barrier
; #define PG8_STAGE(bufoff, gbase, voff) do { _Pragma("unroll") for (int _i = 0; _i < 2; ++_i) \
;         __builtin_amdgcn_global_load_lds((const unsigned*)((const char*)(gbase) + (voff)[_i]), (LAS unsigned*)(lds + (bufoff) + ldsw + _i * 8192), 16, 0, 0); } while (0)
; #define PG8_LDA(dst, b, h) do { _Pragma("unroll") for (int m = 0; m < 4; ++m) _Pragma("unroll") for (int k = 0; k < 2; ++k) dst[m][k] = *(const LAS bf16x8*)(lds + PG8_SA(b, h) + aoff + m * 2048 + k * 1024); } while (0)
; #define PG8_LDB(dst, b, h) do { _Pragma("unroll") for (int n = 0; n < 2; ++n) _Pragma("unroll") for (int k = 0; k < 2; ++k) dst[n][k] = *(const LAS bf16x8*)(lds + PG8_SB(b, h) + boff + n * 2048 + k * 1024); } while (0)
; #define PG8_MMA(ai, bj, At, Bt) do { __builtin_amdgcn_s_setprio(1); _Pragma("unroll") for (int m = 0; m < 4; ++m) _Pragma("unroll") for (int n = 0; n < 2; ++n) _Pragma("unroll") for (int k = 0; k < 2; ++k) \
;         acc[ai][bj][m][n] = __builtin_amdgcn_mfma_f32_16x16x32_bf16(Bt[n][k], At[m][k], acc[ai][bj][m][n], 0, 0, 0); __builtin_amdgcn_s_setprio(0); } while (0)
; #define PG8_WAIT_V(n) asm volatile("s_waitcnt vmcnt(" #n ")" ::: "memory")
; #define PG8_WAIT_L(n) asm volatile("s_waitcnt lgkmcnt(" #n ")" ::: "memory")
; #define PG8_BAR __builtin_amdgcn_s_barrier()
; #define PG8_SCHED __builtin_amdgcn_sched_barrier(0)
; template <class Epi>
; __device__ __forceinline__ void gemm_phase(LAS unsigned char* lds, const Gemm g, const StaticOrder& S, const Epi& E) {
;     ...
;             PG8_WAIT_V(6); PG8_BAR; PG8_MMA(1, 1, At, B1); PG8_BAR;
;             PG8_LDB(B0, 1, 0); PG8_SCHED; PG8_LDA(At, 1, 0); PG8_STAGE(PG8_SA(0, 1), a2 + hstep, voffA);
;             PG8_WAIT_L(8); PG8_BAR; PG8_WAIT_L(0); PG8_MMA(0, 0, At, B0); PG8_BAR; PG8_SCHED;
;             PG8_LDB(B1, 1, 1); PG8_STAGE(PG8_SB(1, 0), b3, voffB);
;             PG8_BAR; PG8_WAIT_L(0); PG8_MMA(0, 1, At, B1); PG8_BAR;
;             PG8_LDA(At, 1, 1); PG8_STAGE(PG8_SA(1, 0), a3, voffA);
	v_mfma_f32_16x16x32_bf16 v[44:47], v[220:223], v[188:191], v[44:47]
	v_mfma_f32_16x16x32_bf16 v[40:43], v[228:231], v[188:191], v[40:43]
	v_mfma_f32_16x16x32_bf16 v[28:31], v[220:223], v[196:199], v[28:31]
	v_mfma_f32_16x16x32_bf16 v[24:27], v[228:231], v[196:199], v[24:27]
	v_mfma_f32_16x16x32_bf16 v[20:23], v[220:223], v[204:207], v[20:23]
	v_mfma_f32_16x16x32_bf16 v[16:19], v[228:231], v[204:207], v[16:19]
	v_mfma_f32_16x16x32_bf16 v[4:7], v[220:223], v[212:215], v[4:7]
	v_mfma_f32_16x16x32_bf16 v[0:3], v[228:231], v[212:215], v[0:3]
	v_mfma_f32_16x16x32_bf16 v[44:47], v[224:227], v[192:195], v[44:47]
	v_mfma_f32_16x16x32_bf16 v[40:43], v[232:235], v[192:195], v[40:43]
	v_mfma_f32_16x16x32_bf16 v[28:31], v[224:227], v[200:203], v[28:31]
	v_mfma_f32_16x16x32_bf16 v[24:27], v[232:235], v[200:203], v[24:27]
	v_mfma_f32_16x16x32_bf16 v[20:23], v[224:227], v[208:211], v[20:23]
	v_mfma_f32_16x16x32_bf16 v[16:19], v[232:235], v[208:211], v[16:19]
	v_mfma_f32_16x16x32_bf16 v[4:7], v[224:227], v[216:219], v[4:7]
	v_mfma_f32_16x16x32_bf16 v[0:3], v[232:235], v[216:219], v[0:3]
	s_add_i32 s68, 0, 0x18000
	v_add_u32_e32 v144, s68, v135
	s_barrier
	ds_read_b128 v[154:157], v144
	ds_read_b128 v[176:179], v144 offset:1024
	ds_read_b128 v[180:183], v144 offset:2048
	ds_read_b128 v[184:187], v144 offset:3072
	s_add_u32 s28, s28, 0x80000
	s_addc_u32 s29, s29, 0
	s_mov_b32 m0, s44
	ds_read_b128 v[188:191], v174 offset:32768
	ds_read_b128 v[192:195], v174 offset:33792
	ds_read_b128 v[196:199], v174 offset:34816
	ds_read_b128 v[200:203], v174 offset:35840
	ds_read_b128 v[204:207], v174 offset:36864
	ds_read_b128 v[208:211], v174 offset:37888
	ds_read_b128 v[212:215], v174 offset:38912
	ds_read_b128 v[216:219], v174 offset:39936
	global_load_lds_dwordx4 v142, s[28:29]
	s_mov_b32 m0, s45
	s_nop 0
	global_load_lds_dwordx4 v138, s[28:29]
	s_waitcnt lgkmcnt(8)
	s_barrier
	s_waitcnt lgkmcnt(0)
	s_waitcnt lgkmcnt(0)
	v_mfma_f32_16x16x32_bf16 v[124:127], v[154:157], v[188:191], v[124:127]
	v_mfma_f32_16x16x32_bf16 v[120:123], v[180:183], v[188:191], v[120:123]
	v_mfma_f32_16x16x32_bf16 v[116:119], v[154:157], v[196:199], v[116:119]
	v_mfma_f32_16x16x32_bf16 v[112:115], v[180:183], v[196:199], v[112:115]
	v_mfma_f32_16x16x32_bf16 v[100:103], v[154:157], v[204:207], v[100:103]
	v_mfma_f32_16x16x32_bf16 v[96:99], v[180:183], v[204:207], v[96:99]
	v_mfma_f32_16x16x32_bf16 v[76:79], v[154:157], v[212:215], v[76:79]
	v_mfma_f32_16x16x32_bf16 v[72:75], v[180:183], v[212:215], v[72:75]
	v_mfma_f32_16x16x32_bf16 v[124:127], v[176:179], v[192:195], v[124:127]
	v_mfma_f32_16x16x32_bf16 v[120:123], v[184:187], v[192:195], v[120:123]
	v_mfma_f32_16x16x32_bf16 v[116:119], v[176:179], v[200:203], v[116:119]
	v_mfma_f32_16x16x32_bf16 v[112:115], v[184:187], v[200:203], v[112:115]
	v_mfma_f32_16x16x32_bf16 v[100:103], v[176:179], v[208:211], v[100:103]
	v_mfma_f32_16x16x32_bf16 v[96:99], v[184:187], v[208:211], v[96:99]
	v_mfma_f32_16x16x32_bf16 v[76:79], v[176:179], v[216:219], v[76:79]
	v_mfma_f32_16x16x32_bf16 v[72:75], v[184:187], v[216:219], v[72:75]
	s_barrier
	s_add_i32 s28, 0, 0x1c000
	s_add_i32 s29, s68, s35
	v_add_u32_e32 v144, s28, v135
	v_lshl_add_u64 v[236:237], v[236:237], 0, s[16:17]
	s_mov_b32 m0, s29
	ds_read_b128 v[220:223], v144
	ds_read_b128 v[224:227], v144 offset:1024
	ds_read_b128 v[228:231], v144 offset:2048
	ds_read_b128 v[232:235], v144 offset:3072
	global_load_lds_dwordx4 v[236:237], off
	v_lshl_add_u64 v[236:237], v[238:239], 0, s[16:17]
	s_add_i32 m0, s29, 0x2000
	s_nop 0
	global_load_lds_dwordx4 v[236:237], off
	s_barrier
	s_waitcnt lgkmcnt(0)
	s_waitcnt lgkmcnt(0)
	v_mfma_f32_16x16x32_bf16 v[108:111], v[220:223], v[188:191], v[108:111]
	v_mfma_f32_16x16x32_bf16 v[104:107], v[228:231], v[188:191], v[104:107]
	v_mfma_f32_16x16x32_bf16 v[92:95], v[220:223], v[196:199], v[92:95]
	v_mfma_f32_16x16x32_bf16 v[88:91], v[228:231], v[196:199], v[88:91]
	v_mfma_f32_16x16x32_bf16 v[84:87], v[220:223], v[204:207], v[84:87]
	v_mfma_f32_16x16x32_bf16 v[80:83], v[228:231], v[204:207], v[80:83]
	v_mfma_f32_16x16x32_bf16 v[68:71], v[220:223], v[212:215], v[68:71]
	v_mfma_f32_16x16x32_bf16 v[64:67], v[228:231], v[212:215], v[64:67]
	v_mfma_f32_16x16x32_bf16 v[108:111], v[224:227], v[192:195], v[108:111]
	v_mfma_f32_16x16x32_bf16 v[104:107], v[232:235], v[192:195], v[104:107]
	v_mfma_f32_16x16x32_bf16 v[92:95], v[224:227], v[200:203], v[92:95]
	v_mfma_f32_16x16x32_bf16 v[88:91], v[232:235], v[200:203], v[88:91]
	v_mfma_f32_16x16x32_bf16 v[84:87], v[224:227], v[208:211], v[84:87]
	v_mfma_f32_16x16x32_bf16 v[80:83], v[232:235], v[208:211], v[80:83]
	v_mfma_f32_16x16x32_bf16 v[68:71], v[224:227], v[216:219], v[68:71]
	v_mfma_f32_16x16x32_bf16 v[64:67], v[232:235], v[216:219], v[64:67]
	s_mov_b32 m0, s48
	v_lshl_add_u64 v[236:237], v[240:241], 0, s[16:17]
	s_barrier
	ds_read_b128 v[188:191], v174 offset:49152
	ds_read_b128 v[192:195], v174 offset:50176
	ds_read_b128 v[196:199], v174 offset:51200
	ds_read_b128 v[200:203], v174 offset:52224
	ds_read_b128 v[204:207], v174 offset:53248
	ds_read_b128 v[208:211], v174 offset:54272
	ds_read_b128 v[212:215], v174 offset:55296
	ds_read_b128 v[216:219], v174 offset:56320
	global_load_lds_dwordx4 v[236:237], off
	v_lshl_add_u64 v[236:237], v[242:243], 0, s[16:17]
	s_mov_b32 m0, s49
	s_nop 0
	global_load_lds_dwordx4 v[236:237], off
	s_barrier
; __device__ __forceinline__ unsigned pk_bf16(float lo, float hi) { const f32x2 v = (f32x2){lo, hi}; const bf16v2 b = __builtin_convertvector(v, bf16v2); return __builtin_bit_cast(unsigned, b); }
; #define PG8_STAGE(bufoff, gbase, voff) do { _Pragma("unroll") for (int _i = 0; _i < 2; ++_i) \
;         __builtin_amdgcn_global_load_lds((const unsigned*)((const char*)(gbase) + (voff)[_i]), (LAS unsigned*)(lds + (bufoff) + ldsw + _i * 8192), 16, 0, 0); } while (0)
; #define PG8_BAR __builtin_amdgcn_s_barrier()
; template <class Epi>
; __device__ __forceinline__ void gemm_phase(LAS unsigned char* lds, const Gemm g, const StaticOrder& S, const Epi& E) {
;     ...
;             PG8_BAR; PG8_WAIT_L(0); PG8_MMA(0, 1, At, B1); PG8_BAR;
;             PG8_LDA(At, 1, 1); PG8_STAGE(PG8_SA(1, 0), a3, voffA);
;             PG8_BAR; PG8_WAIT_L(0); PG8_MMA(1, 0, At, B0); PG8_BAR; PG8_SCHED;
;             PG8_STAGE(PG8_SB(1, 1), b3 + hstep, voffB);
;             PG8_WAIT_V(6); PG8_BAR; PG8_MMA(1, 1, At, B1); PG8_BAR;
;     __device__ __forceinline__ void operator()(const f32x4 (&acc)[2][2][4][2], const pg8::Unit& u, int wr, int wc, int fr, int fq) const {
;         const int row0 = u.pm * 256 + wr * 64 + fr, col0 = u.pn * 256 + wc * 32 + 8 * fq;
; #pragma unroll
;         for (int ai = 0; ai < 2; ++ai)
; #pragma unroll
;             for (int m = 0; m < 4; ++m) {
;                 const int row = row0 + ai * 128 + m * 16;
;                 bf16_t* rowp = Z + (size_t)row * LDZ + col0;
;                 const bool last = ((row & 63) == 63) && (row >= MP || (row & (SEQ - 1)) == SEQ - 1);
; #pragma unroll
;                 for (int bj = 0; bj < 2; ++bj) {
;                     const f32x4 v0 = acc[ai][bj][m][0], v1 = acc[ai][bj][m][1];
;                     u32x4 w; w.x = pk_bf16(v0[0], v0[1]); w.y = pk_bf16(v0[2], v0[3]); w.z = pk_bf16(v1[0], v1[1]); w.w = pk_bf16(v1[2], v1[3]);
;                     *(u32x4*)(rowp + bj * 128) = w;
;                     if (last) {
;                         const int c = col0 + bj * 128 - ZC_S;
;                         if (c >= 0 && c < NSHIFT) {
;                             float* o = row < MP ? out + O_SHP + (size_t)(row >> 13) * NSHIFT + c : out + O_SHS + (size_t)((row - MP) >> 6) * NSHIFT + c;
;                             *(f32x4*)o = v0; *(f32x4*)(o + 4) = v1;
;                         }
;                     }
;                 }
	s_waitcnt lgkmcnt(0)
	s_waitcnt lgkmcnt(0)
	v_mfma_f32_16x16x32_bf16 v[60:63], v[154:157], v[188:191], v[60:63]
	v_mfma_f32_16x16x32_bf16 v[56:59], v[180:183], v[188:191], v[56:59]
	v_mfma_f32_16x16x32_bf16 v[52:55], v[154:157], v[196:199], v[52:55]
	v_mfma_f32_16x16x32_bf16 v[48:51], v[180:183], v[196:199], v[48:51]
	v_mfma_f32_16x16x32_bf16 v[36:39], v[154:157], v[204:207], v[36:39]
	v_mfma_f32_16x16x32_bf16 v[32:35], v[180:183], v[204:207], v[32:35]
	v_mfma_f32_16x16x32_bf16 v[12:15], v[154:157], v[212:215], v[12:15]
	v_mfma_f32_16x16x32_bf16 v[8:11], v[180:183], v[212:215], v[8:11]
	v_mfma_f32_16x16x32_bf16 v[60:63], v[176:179], v[192:195], v[60:63]
	v_mfma_f32_16x16x32_bf16 v[56:59], v[184:187], v[192:195], v[56:59]
	v_mfma_f32_16x16x32_bf16 v[52:55], v[176:179], v[200:203], v[52:55]
	v_mfma_f32_16x16x32_bf16 v[48:51], v[184:187], v[200:203], v[48:51]
	v_mfma_f32_16x16x32_bf16 v[36:39], v[176:179], v[208:211], v[36:39]
	v_mfma_f32_16x16x32_bf16 v[32:35], v[184:187], v[208:211], v[32:35]
	v_mfma_f32_16x16x32_bf16 v[12:15], v[176:179], v[216:219], v[12:15]
	v_mfma_f32_16x16x32_bf16 v[8:11], v[184:187], v[216:219], v[8:11]
	s_barrier
	s_add_u32 s26, s26, 0x80080
	s_addc_u32 s27, s27, 0
	s_add_i32 s28, s28, s35
	s_mov_b32 m0, s28
	s_nop 0
	global_load_lds_dwordx4 v140, s[26:27]
	s_add_i32 m0, s28, 0x2000
	s_nop 0
	global_load_lds_dwordx4 v136, s[26:27]
	s_waitcnt vmcnt(6)
	s_barrier
	v_mfma_f32_16x16x32_bf16 v[44:47], v[220:223], v[188:191], v[44:47]
	v_mfma_f32_16x16x32_bf16 v[40:43], v[228:231], v[188:191], v[40:43]
	v_mfma_f32_16x16x32_bf16 v[28:31], v[220:223], v[196:199], v[28:31]
	v_mfma_f32_16x16x32_bf16 v[24:27], v[228:231], v[196:199], v[24:27]
	v_mfma_f32_16x16x32_bf16 v[20:23], v[220:223], v[204:207], v[20:23]
	v_mfma_f32_16x16x32_bf16 v[16:19], v[228:231], v[204:207], v[16:19]
	v_mfma_f32_16x16x32_bf16 v[4:7], v[220:223], v[212:215], v[4:7]
	v_mfma_f32_16x16x32_bf16 v[0:3], v[228:231], v[212:215], v[0:3]
	v_mfma_f32_16x16x32_bf16 v[44:47], v[224:227], v[192:195], v[44:47]
	v_mfma_f32_16x16x32_bf16 v[40:43], v[232:235], v[192:195], v[40:43]
	v_mfma_f32_16x16x32_bf16 v[28:31], v[224:227], v[200:203], v[28:31]
	v_mfma_f32_16x16x32_bf16 v[24:27], v[232:235], v[200:203], v[24:27]
	v_mfma_f32_16x16x32_bf16 v[20:23], v[224:227], v[208:211], v[20:23]
	v_mfma_f32_16x16x32_bf16 v[16:19], v[232:235], v[208:211], v[16:19]
	v_mfma_f32_16x16x32_bf16 v[4:7], v[224:227], v[216:219], v[4:7]
	v_mfma_f32_16x16x32_bf16 v[0:3], v[232:235], v[216:219], v[0:3]
	s_add_i32 s67, s67, 2
	s_add_u32 s12, s12, 0x100
	s_addc_u32 s13, s13, 0
	s_add_u32 s65, s65, 0x100
	s_addc_u32 s66, s66, 0
	s_cmp_gt_u32 s67, 29
	s_barrier
	s_cbranch_scc0 .LBB0_80
	s_lshl_b32 s7, s31, 8
	s_add_i32 s7, s7, s47
	v_lshl_or_b32 v156, s30, 8, v172
	s_add_i32 s12, s7, 0xffff8000
	v_or_b32_e32 v176, s7, v161
	v_ashrrev_i32_e32 v157, 31, v156
	s_lshr_b32 s63, s12, 6
	s_ashr_i32 s12, s7, 13
	v_mov_b64_e32 v[178:179], s[14:15]
	s_mul_i32 s26, s12, 0xc80
	v_mad_i64_i32 v[180:181], s[12:13], v176, s58, v[178:179]
	v_lshlrev_b64 v[154:155], 1, v[156:157]
	v_cvt_pk_bf16_f32 v108, v108, v109
	v_cvt_pk_bf16_f32 v109, v110, v111
	v_cvt_pk_bf16_f32 v110, v104, v105
	v_or_b32_e32 v104, 16, v176
	v_cvt_pk_bf16_f32 v92, v92, v93
	v_cvt_pk_bf16_f32 v93, v94, v95
	v_cvt_pk_bf16_f32 v94, v88, v89
	v_or_b32_e32 v88, 32, v176
	v_cvt_pk_bf16_f32 v84, v84, v85
	v_cvt_pk_bf16_f32 v85, v86, v87
	v_cvt_pk_bf16_f32 v87, v82, v83
	v_or_b32_e32 v82, 48, v176
	v_lshl_add_u64 v[180:181], v[180:181], 0, v[154:155]
	v_cvt_pk_bf16_f32 v111, v106, v107
	v_mad_i64_i32 v[104:105], s[12:13], v104, s58, v[178:179]
	v_mad_i64_i32 v[88:89], s[12:13], v88, s58, v[178:179]
	v_cvt_pk_bf16_f32 v86, v80, v81
	v_mad_i64_i32 v[80:81], s[12:13], v82, s58, v[178:179]
	v_bitop3_b32 v83, v176, s60, 48 bitop3:0xc8
	global_store_dwordx4 v[180:181], v[108:111], off offset:256
	v_cvt_pk_bf16_f32 v95, v90, v91
	v_cmp_lt_i32_e32 vcc, s59, v82
	v_lshl_add_u64 v[108:109], v[104:105], 0, v[154:155]
	v_cmp_eq_u32_e64 s[12:13], s60, v83
	global_store_dwordx4 v[108:109], v[92:95], off offset:256
	s_or_b64 s[12:13], vcc, s[12:13]
	s_mul_hi_u32 s25, s63, 0x3200
	v_lshl_add_u64 v[92:93], v[88:89], 0, v[154:155]
	s_mulk_i32 s63, 0x3200
	s_ashr_i32 s27, s26, 31
	v_cvt_pk_bf16_f32 v124, v124, v125
	v_cvt_pk_bf16_f32 v125, v126, v127
	v_cvt_pk_bf16_f32 v126, v120, v121
	v_cvt_pk_bf16_f32 v127, v122, v123
	v_cvt_pk_bf16_f32 v104, v116, v117
	v_cvt_pk_bf16_f32 v105, v118, v119
	v_cvt_pk_bf16_f32 v106, v112, v113
	v_cvt_pk_bf16_f32 v107, v114, v115
	v_cvt_pk_bf16_f32 v88, v100, v101
	v_cvt_pk_bf16_f32 v89, v102, v103
	v_cvt_pk_bf16_f32 v90, v96, v97
	v_cvt_pk_bf16_f32 v91, v98, v99
	global_store_dwordx4 v[92:93], v[84:87], off offset:256
	v_lshl_add_u64 v[80:81], v[80:81], 0, v[154:155]
	s_and_b64 s[28:29], s[8:9], s[12:13]
	v_cmp_gt_i32_e32 vcc, s50, v82
	v_cvt_pk_bf16_f32 v82, v76, v77
	v_cvt_pk_bf16_f32 v83, v78, v79
	v_cvt_pk_bf16_f32 v84, v72, v73
	v_cvt_pk_bf16_f32 v85, v74, v75
	v_add_u32_e32 v144, 0xfffff400, v156
	global_store_dwordx4 v[180:181], v[124:127], off
	global_store_dwordx4 v[108:109], v[104:107], off
	global_store_dwordx4 v[92:93], v[88:91], off
	global_store_dwordx4 v[80:81], v[82:85], off
	s_and_saveexec_b64 s[30:31], s[28:29]
	s_cbranch_execz .LBB0_84
	v_cmp_gt_u32_e64 s[12:13], s57, v144
	s_and_b64 exec, exec, s[12:13]
	s_cbranch_execz .LBB0_84
	s_lshl_b64 s[12:13], s[26:27], 2
	s_add_u32 s12, s22, s12
	s_addc_u32 s13, s23, s13
	s_add_u32 s64, s51, s63
	s_addc_u32 s65, s52, s25
	v_mov_b32_e32 v82, s65
	v_mov_b32_e32 v83, s13
	v_cndmask_b32_e32 v83, v82, v83, vcc
	v_mov_b32_e32 v82, s64
	v_mov_b32_e32 v84, s12
	v_cndmask_b32_e32 v82, v82, v84, vcc
	v_lshl_add_u64 v[82:83], v[144:145], 2, v[82:83]
	global_store_dwordx4 v[82:83], v[76:79], off
	global_store_dwordx4 v[82:83], v[72:75], off offset:16

; #define PG8_STAGE(bufoff, gbase, voff) do { _Pragma("unroll") for (int _i = 0; _i < 2; ++_i) \
;         __builtin_amdgcn_global_load_lds((const unsigned*)((const char*)(gbase) + (voff)[_i]), (LAS unsigned*)(lds + (bufoff) + ldsw + _i * 8192), 16, 0, 0); } while (0)
; #define PG8_LDA(dst, b, h) do { _Pragma("unroll") for (int m = 0; m < 4; ++m) _Pragma("unroll") for (int k = 0; k < 2; ++k) dst[m][k] = *(const LAS bf16x8*)(lds + PG8_SA(b, h) + aoff + m * 2048 + k * 1024); } while (0)
; #define PG8_LDB(dst, b, h) do { _Pragma("unroll") for (int n = 0; n < 2; ++n) _Pragma("unroll") for (int k = 0; k < 2; ++k) dst[n][k] = *(const LAS bf16x8*)(lds + PG8_SB(b, h) + boff + n * 2048 + k * 1024); } while (0)
; #define PG8_MMA(ai, bj, At, Bt) do { __builtin_amdgcn_s_setprio(1); _Pragma("unroll") for (int m = 0; m < 4; ++m) _Pragma("unroll") for (int n = 0; n < 2; ++n) _Pragma("unroll") for (int k = 0; k < 2; ++k) \
;         acc[ai][bj][m][n] = __builtin_amdgcn_mfma_f32_16x16x32_bf16(Bt[n][k], At[m][k], acc[ai][bj][m][n], 0, 0, 0); __builtin_amdgcn_s_setprio(0); } while (0)
; #define PG8_WAIT_V(n) asm volatile("s_waitcnt vmcnt(" #n ")" ::: "memory")
; #define PG8_WAIT_L(n) asm volatile("s_waitcnt lgkmcnt(" #n ")" ::: "memory")
; #define PG8_BAR __builtin_amdgcn_s_barrier()
; #define PG8_SCHED __builtin_amdgcn_sched_barrier(0)
; template <class Epi>
; __device__ __forceinline__ void gemm_phase(LAS unsigned char* lds, const Gemm g, const StaticOrder& S, const Epi& E) {
;     ...
;             PG8_LDB(B0, 0, 0); PG8_SCHED; PG8_LDA(At, 0, 0); PG8_STAGE(PG8_SA(1, 1), a1 + hstep, voffA);
;             PG8_WAIT_L(8); PG8_BAR; PG8_WAIT_L(0); PG8_MMA(0, 0, At, B0); PG8_BAR; PG8_SCHED;
;             PG8_LDB(B1, 0, 1); PG8_STAGE(PG8_SB(0, 0), b2, voffB);
;             PG8_BAR; PG8_WAIT_L(0); PG8_MMA(0, 1, At, B1); PG8_BAR;
;             PG8_LDA(At, 0, 1); PG8_STAGE(PG8_SA(0, 0), a2, voffA);
;             PG8_BAR; PG8_WAIT_L(0); PG8_MMA(1, 0, At, B0); PG8_BAR; PG8_SCHED;
;             PG8_STAGE(PG8_SB(0, 1), b2 + hstep, voffB);
;             PG8_WAIT_V(6); PG8_BAR; PG8_MMA(1, 1, At, B1); PG8_BAR;
.LBB0_559:
	ds_read_b128 v[156:159], v133
	ds_read_b128 v[160:163], v133 offset:1024
	ds_read_b128 v[164:167], v133 offset:2048
	ds_read_b128 v[168:171], v133 offset:3072
	s_add_u32 s34, s30, 0xfff80080
	s_addc_u32 s35, s31, -1
	s_cmp_eq_u32 s65, 28
	s_cselect_b32 s41, s25, s35
	s_cselect_b32 s40, s61, s34
	s_cselect_b32 s35, s23, s64
	s_cselect_b32 s34, s62, s63
	s_add_i32 m0, s21, 0xc000
	ds_read_b128 v[172:175], v153
	ds_read_b128 v[176:179], v153 offset:1024
	ds_read_b128 v[180:183], v153 offset:2048
	ds_read_b128 v[184:187], v153 offset:3072
	ds_read_b128 v[188:191], v153 offset:4096
	ds_read_b128 v[192:195], v153 offset:5120
	ds_read_b128 v[196:199], v153 offset:6144
	ds_read_b128 v[200:203], v153 offset:7168
	global_load_lds_dwordx4 v142, s[30:31]
	s_add_i32 m0, s21, 0xe000
	s_nop 0
	global_load_lds_dwordx4 v144, s[30:31]
	s_waitcnt lgkmcnt(8)
	s_barrier
	s_waitcnt lgkmcnt(0)
	s_waitcnt lgkmcnt(0)
	v_mfma_f32_16x16x32_bf16 v[124:127], v[156:159], v[172:175], v[124:127]
	v_mfma_f32_16x16x32_bf16 v[120:123], v[164:167], v[172:175], v[120:123]
	v_mfma_f32_16x16x32_bf16 v[116:119], v[156:159], v[180:183], v[116:119]
	v_mfma_f32_16x16x32_bf16 v[112:115], v[164:167], v[180:183], v[112:115]
	v_mfma_f32_16x16x32_bf16 v[100:103], v[156:159], v[188:191], v[100:103]
	v_mfma_f32_16x16x32_bf16 v[96:99], v[164:167], v[188:191], v[96:99]
	v_mfma_f32_16x16x32_bf16 v[84:87], v[156:159], v[196:199], v[84:87]
	v_mfma_f32_16x16x32_bf16 v[80:83], v[164:167], v[196:199], v[80:83]
	v_mfma_f32_16x16x32_bf16 v[124:127], v[160:163], v[176:179], v[124:127]
	v_mfma_f32_16x16x32_bf16 v[120:123], v[168:171], v[176:179], v[120:123]
	v_mfma_f32_16x16x32_bf16 v[116:119], v[160:163], v[184:187], v[116:119]
	v_mfma_f32_16x16x32_bf16 v[112:115], v[168:171], v[184:187], v[112:115]
	v_mfma_f32_16x16x32_bf16 v[100:103], v[160:163], v[192:195], v[100:103]
	v_mfma_f32_16x16x32_bf16 v[96:99], v[168:171], v[192:195], v[96:99]
	v_mfma_f32_16x16x32_bf16 v[84:87], v[160:163], v[200:203], v[84:87]
	v_mfma_f32_16x16x32_bf16 v[80:83], v[168:171], v[200:203], v[80:83]
	s_barrier
	s_add_i32 s66, s54, s43
	v_lshl_add_u64 v[220:221], s[34:35], 0, v[138:139]
	s_mov_b32 m0, s66
	ds_read_b128 v[204:207], v154
	ds_read_b128 v[208:211], v154 offset:1024
	ds_read_b128 v[212:215], v154 offset:2048
	ds_read_b128 v[216:219], v154 offset:3072
	global_load_lds_dwordx4 v[220:221], off
	v_lshl_add_u64 v[222:223], s[34:35], 0, v[134:135]
	s_add_i32 m0, s66, 0x2000
	s_nop 0
	global_load_lds_dwordx4 v[222:223], off
	s_barrier
	s_waitcnt lgkmcnt(0)
	s_waitcnt lgkmcnt(0)
	v_mfma_f32_16x16x32_bf16 v[108:111], v[204:207], v[172:175], v[108:111]
	v_mfma_f32_16x16x32_bf16 v[104:107], v[212:215], v[172:175], v[104:107]
	v_mfma_f32_16x16x32_bf16 v[92:95], v[204:207], v[180:183], v[92:95]
	v_mfma_f32_16x16x32_bf16 v[88:91], v[212:215], v[180:183], v[88:91]
	v_mfma_f32_16x16x32_bf16 v[76:79], v[204:207], v[188:191], v[76:79]
	v_mfma_f32_16x16x32_bf16 v[72:75], v[212:215], v[188:191], v[72:75]
	v_mfma_f32_16x16x32_bf16 v[68:71], v[204:207], v[196:199], v[68:71]
	v_mfma_f32_16x16x32_bf16 v[64:67], v[212:215], v[196:199], v[64:67]
	v_mfma_f32_16x16x32_bf16 v[108:111], v[208:211], v[176:179], v[108:111]
	v_mfma_f32_16x16x32_bf16 v[104:107], v[216:219], v[176:179], v[104:107]
	v_mfma_f32_16x16x32_bf16 v[92:95], v[208:211], v[184:187], v[92:95]
	v_mfma_f32_16x16x32_bf16 v[88:91], v[216:219], v[184:187], v[88:91]
	v_mfma_f32_16x16x32_bf16 v[76:79], v[208:211], v[192:195], v[76:79]
	v_mfma_f32_16x16x32_bf16 v[72:75], v[216:219], v[192:195], v[72:75]
	v_mfma_f32_16x16x32_bf16 v[68:71], v[208:211], v[200:203], v[68:71]
	v_mfma_f32_16x16x32_bf16 v[64:67], v[216:219], v[200:203], v[64:67]
	s_mov_b32 m0, s21
	v_lshl_add_u64 v[224:225], s[40:41], 0, v[140:141]
	s_barrier
	ds_read_b128 v[172:175], v153 offset:16384
	ds_read_b128 v[176:179], v153 offset:17408
	ds_read_b128 v[180:183], v153 offset:18432
	ds_read_b128 v[184:187], v153 offset:19456
	ds_read_b128 v[188:191], v153 offset:20480
	ds_read_b128 v[192:195], v153 offset:21504
	ds_read_b128 v[196:199], v153 offset:22528
	ds_read_b128 v[200:203], v153 offset:23552
	global_load_lds_dwordx4 v[224:225], off
	v_lshl_add_u64 v[226:227], s[40:41], 0, v[136:137]
	s_mov_b32 m0, s46
	s_nop 0
	global_load_lds_dwordx4 v[226:227], off
	s_barrier
	s_waitcnt lgkmcnt(0)
	s_waitcnt lgkmcnt(0)
	v_mfma_f32_16x16x32_bf16 v[60:63], v[156:159], v[172:175], v[60:63]
	v_mfma_f32_16x16x32_bf16 v[56:59], v[164:167], v[172:175], v[56:59]
	v_mfma_f32_16x16x32_bf16 v[52:55], v[156:159], v[180:183], v[52:55]
	v_mfma_f32_16x16x32_bf16 v[48:51], v[164:167], v[180:183], v[48:51]
	v_mfma_f32_16x16x32_bf16 v[36:39], v[156:159], v[188:191], v[36:39]
	v_mfma_f32_16x16x32_bf16 v[32:35], v[164:167], v[188:191], v[32:35]
	v_mfma_f32_16x16x32_bf16 v[20:23], v[156:159], v[196:199], v[20:23]
	v_mfma_f32_16x16x32_bf16 v[16:19], v[164:167], v[196:199], v[16:19]
	v_mfma_f32_16x16x32_bf16 v[60:63], v[160:163], v[176:179], v[60:63]
	v_mfma_f32_16x16x32_bf16 v[56:59], v[168:171], v[176:179], v[56:59]
	v_mfma_f32_16x16x32_bf16 v[52:55], v[160:163], v[184:187], v[52:55]
	v_mfma_f32_16x16x32_bf16 v[48:51], v[168:171], v[184:187], v[48:51]
	v_mfma_f32_16x16x32_bf16 v[36:39], v[160:163], v[192:195], v[36:39]
	v_mfma_f32_16x16x32_bf16 v[32:35], v[168:171], v[192:195], v[32:35]
	v_mfma_f32_16x16x32_bf16 v[20:23], v[160:163], v[200:203], v[20:23]
	v_mfma_f32_16x16x32_bf16 v[16:19], v[168:171], v[200:203], v[16:19]
	s_barrier
	s_add_u32 s66, s34, 0x80000
	s_addc_u32 s67, s35, 0
	s_add_i32 s68, s55, s43
	s_mov_b32 m0, s68
	s_nop 0
	global_load_lds_dwordx4 v138, s[66:67]
	s_add_i32 m0, s68, 0x2000
	s_nop 0
	global_load_lds_dwordx4 v134, s[66:67]
	s_waitcnt vmcnt(6)
	s_barrier
; #define PG8_STAGE(bufoff, gbase, voff) do { _Pragma("unroll") for (int _i = 0; _i < 2; ++_i) \
;         __builtin_amdgcn_global_load_lds((const unsigned*)((const char*)(gbase) + (voff)[_i]), (LAS unsigned*)(lds + (bufoff) + ldsw + _i * 8192), 16, 0, 0); } while (0)
; #define PG8_LDA(dst, b, h) do { _Pragma("unroll") for (int m = 0; m < 4; ++m) _Pragma("unroll") for (int k = 0; k < 2; ++k) dst[m][k] = *(const LAS bf16x8*)(lds + PG8_SA(b, h) + aoff + m * 2048 + k * 1024); } while (0)
; #define PG8_LDB(dst, b, h) do { _Pragma("unroll") for (int n = 0; n < 2; ++n) _Pragma("unroll") for (int k = 0; k < 2; ++k) dst[n][k] = *(const LAS bf16x8*)(lds + PG8_SB(b, h) + boff + n * 2048 + k * 1024); } while (0)
; #define PG8_MMA(ai, bj, At, Bt) do { __builtin_amdgcn_s_setprio(1); _Pragma("unroll") for (int m = 0; m < 4; ++m) _Pragma("unroll") for (int n = 0; n < 2; ++n) _Pragma("unroll") for (int k = 0; k < 2; ++k) \
;         acc[ai][bj][m][n] = __builtin_amdgcn_mfma_f32_16x16x32_bf16(Bt[n][k], At[m][k], acc[ai][bj][m][n], 0, 0, 0); __builtin_amdgcn_s_setprio(0); } while (0)
; #define PG8_WAIT_V(n) asm volatile("s_waitcnt vmcnt(" #n ")" ::: "memory")
; #define PG8_WAIT_L(n) asm volatile("s_waitcnt lgkmcnt(" #n ")" ::: "memory")
; #define PG8_BAR __builtin_amdgcn_s_barrier()
; #define PG8_SCHED __builtin_amdgcn_sched_barrier(0)
; template <class Epi>
; __device__ __forceinline__ void gemm_phase(LAS unsigned char* lds, const Gemm g, const StaticOrder& S, const Epi& E) {
;     ...
;             PG8_WAIT_V(6); PG8_BAR; PG8_MMA(1, 1, At, B1); PG8_BAR;
;             PG8_LDB(B0, 1, 0); PG8_SCHED; PG8_LDA(At, 1, 0); PG8_STAGE(PG8_SA(0, 1), a2 + hstep, voffA);
;             PG8_WAIT_L(8); PG8_BAR; PG8_WAIT_L(0); PG8_MMA(0, 0, At, B0); PG8_BAR; PG8_SCHED;
;             PG8_LDB(B1, 1, 1); PG8_STAGE(PG8_SB(1, 0), b3, voffB);
;             PG8_BAR; PG8_WAIT_L(0); PG8_MMA(0, 1, At, B1); PG8_BAR;
;             PG8_LDA(At, 1, 1); PG8_STAGE(PG8_SA(1, 0), a3, voffA);
	v_mfma_f32_16x16x32_bf16 v[44:47], v[204:207], v[172:175], v[44:47]
	v_mfma_f32_16x16x32_bf16 v[40:43], v[212:215], v[172:175], v[40:43]
	v_mfma_f32_16x16x32_bf16 v[28:31], v[204:207], v[180:183], v[28:31]
	v_mfma_f32_16x16x32_bf16 v[24:27], v[212:215], v[180:183], v[24:27]
	v_mfma_f32_16x16x32_bf16 v[12:15], v[204:207], v[188:191], v[12:15]
	v_mfma_f32_16x16x32_bf16 v[8:11], v[212:215], v[188:191], v[8:11]
	v_mfma_f32_16x16x32_bf16 v[4:7], v[204:207], v[196:199], v[4:7]
	v_mfma_f32_16x16x32_bf16 v[0:3], v[212:215], v[196:199], v[0:3]
	v_mfma_f32_16x16x32_bf16 v[44:47], v[208:211], v[176:179], v[44:47]
	v_mfma_f32_16x16x32_bf16 v[40:43], v[216:219], v[176:179], v[40:43]
	v_mfma_f32_16x16x32_bf16 v[28:31], v[208:211], v[184:187], v[28:31]
	v_mfma_f32_16x16x32_bf16 v[24:27], v[216:219], v[184:187], v[24:27]
	v_mfma_f32_16x16x32_bf16 v[12:15], v[208:211], v[192:195], v[12:15]
	v_mfma_f32_16x16x32_bf16 v[8:11], v[216:219], v[192:195], v[8:11]
	v_mfma_f32_16x16x32_bf16 v[4:7], v[208:211], v[200:203], v[4:7]
	v_mfma_f32_16x16x32_bf16 v[0:3], v[216:219], v[200:203], v[0:3]
	s_add_i32 s66, 0, 0x18000
	v_add_u32_e32 v155, s66, v151
	s_barrier
	ds_read_b128 v[156:159], v155
	ds_read_b128 v[160:163], v155 offset:1024
	ds_read_b128 v[164:167], v155 offset:2048
	ds_read_b128 v[168:171], v155 offset:3072
	s_add_u32 s40, s40, 0x80000
	s_addc_u32 s41, s41, 0
	s_mov_b32 m0, s47
	ds_read_b128 v[172:175], v153 offset:32768
	ds_read_b128 v[176:179], v153 offset:33792
	ds_read_b128 v[180:183], v153 offset:34816
	ds_read_b128 v[184:187], v153 offset:35840
	ds_read_b128 v[188:191], v153 offset:36864
	ds_read_b128 v[192:195], v153 offset:37888
	ds_read_b128 v[196:199], v153 offset:38912
	ds_read_b128 v[200:203], v153 offset:39936
	global_load_lds_dwordx4 v140, s[40:41]
	s_mov_b32 m0, s48
	s_nop 0
	global_load_lds_dwordx4 v136, s[40:41]
	s_waitcnt lgkmcnt(8)
	s_barrier
	s_waitcnt lgkmcnt(0)
	s_waitcnt lgkmcnt(0)
	v_mfma_f32_16x16x32_bf16 v[124:127], v[156:159], v[172:175], v[124:127]
	v_mfma_f32_16x16x32_bf16 v[120:123], v[164:167], v[172:175], v[120:123]
	v_mfma_f32_16x16x32_bf16 v[116:119], v[156:159], v[180:183], v[116:119]
	v_mfma_f32_16x16x32_bf16 v[112:115], v[164:167], v[180:183], v[112:115]
	v_mfma_f32_16x16x32_bf16 v[100:103], v[156:159], v[188:191], v[100:103]
	v_mfma_f32_16x16x32_bf16 v[96:99], v[164:167], v[188:191], v[96:99]
	v_mfma_f32_16x16x32_bf16 v[84:87], v[156:159], v[196:199], v[84:87]
	v_mfma_f32_16x16x32_bf16 v[80:83], v[164:167], v[196:199], v[80:83]
	v_mfma_f32_16x16x32_bf16 v[124:127], v[160:163], v[176:179], v[124:127]
	v_mfma_f32_16x16x32_bf16 v[120:123], v[168:171], v[176:179], v[120:123]
	v_mfma_f32_16x16x32_bf16 v[116:119], v[160:163], v[184:187], v[116:119]
	v_mfma_f32_16x16x32_bf16 v[112:115], v[168:171], v[184:187], v[112:115]
	v_mfma_f32_16x16x32_bf16 v[100:103], v[160:163], v[192:195], v[100:103]
	v_mfma_f32_16x16x32_bf16 v[96:99], v[168:171], v[192:195], v[96:99]
	v_mfma_f32_16x16x32_bf16 v[84:87], v[160:163], v[200:203], v[84:87]
	v_mfma_f32_16x16x32_bf16 v[80:83], v[168:171], v[200:203], v[80:83]
	s_barrier
	s_add_i32 s40, 0, 0x1c000
	s_add_i32 s41, s66, s43
	v_add_u32_e32 v155, s40, v151
	v_lshl_add_u64 v[220:221], v[220:221], 0, s[12:13]
	s_mov_b32 m0, s41
	ds_read_b128 v[204:207], v155
	ds_read_b128 v[208:211], v155 offset:1024
	ds_read_b128 v[212:215], v155 offset:2048
	ds_read_b128 v[216:219], v155 offset:3072
	global_load_lds_dwordx4 v[220:221], off
	v_lshl_add_u64 v[220:221], v[222:223], 0, s[12:13]
	s_add_i32 m0, s41, 0x2000
	s_nop 0
	global_load_lds_dwordx4 v[220:221], off
	s_barrier
	s_waitcnt lgkmcnt(0)
	s_waitcnt lgkmcnt(0)
	v_mfma_f32_16x16x32_bf16 v[108:111], v[204:207], v[172:175], v[108:111]
	v_mfma_f32_16x16x32_bf16 v[104:107], v[212:215], v[172:175], v[104:107]
	v_mfma_f32_16x16x32_bf16 v[92:95], v[204:207], v[180:183], v[92:95]
	v_mfma_f32_16x16x32_bf16 v[88:91], v[212:215], v[180:183], v[88:91]
	v_mfma_f32_16x16x32_bf16 v[76:79], v[204:207], v[188:191], v[76:79]
	v_mfma_f32_16x16x32_bf16 v[72:75], v[212:215], v[188:191], v[72:75]
	v_mfma_f32_16x16x32_bf16 v[68:71], v[204:207], v[196:199], v[68:71]
	v_mfma_f32_16x16x32_bf16 v[64:67], v[212:215], v[196:199], v[64:67]
	v_mfma_f32_16x16x32_bf16 v[108:111], v[208:211], v[176:179], v[108:111]
	v_mfma_f32_16x16x32_bf16 v[104:107], v[216:219], v[176:179], v[104:107]
	v_mfma_f32_16x16x32_bf16 v[92:95], v[208:211], v[184:187], v[92:95]
	v_mfma_f32_16x16x32_bf16 v[88:91], v[216:219], v[184:187], v[88:91]
	v_mfma_f32_16x16x32_bf16 v[76:79], v[208:211], v[192:195], v[76:79]
	v_mfma_f32_16x16x32_bf16 v[72:75], v[216:219], v[192:195], v[72:75]
	v_mfma_f32_16x16x32_bf16 v[68:71], v[208:211], v[200:203], v[68:71]
	v_mfma_f32_16x16x32_bf16 v[64:67], v[216:219], v[200:203], v[64:67]
	s_mov_b32 m0, s50
	v_lshl_add_u64 v[220:221], v[224:225], 0, s[12:13]
	s_barrier
	ds_read_b128 v[172:175], v153 offset:49152
	ds_read_b128 v[176:179], v153 offset:50176
	ds_read_b128 v[180:183], v153 offset:51200
	ds_read_b128 v[184:187], v153 offset:52224
	ds_read_b128 v[188:191], v153 offset:53248
	ds_read_b128 v[192:195], v153 offset:54272
	ds_read_b128 v[196:199], v153 offset:55296
	ds_read_b128 v[200:203], v153 offset:56320
	global_load_lds_dwordx4 v[220:221], off
	v_lshl_add_u64 v[220:221], v[226:227], 0, s[12:13]
	s_mov_b32 m0, s51
	s_nop 0
	global_load_lds_dwordx4 v[220:221], off
	s_barrier
; #define PG8_STAGE(bufoff, gbase, voff) do { _Pragma("unroll") for (int _i = 0; _i < 2; ++_i) \
;         __builtin_amdgcn_global_load_lds((const unsigned*)((const char*)(gbase) + (voff)[_i]), (LAS unsigned*)(lds + (bufoff) + ldsw + _i * 8192), 16, 0, 0); } while (0)
; #define PG8_LDA(dst, b, h) do { _Pragma("unroll") for (int m = 0; m < 4; ++m) _Pragma("unroll") for (int k = 0; k < 2; ++k) dst[m][k] = *(const LAS bf16x8*)(lds + PG8_SA(b, h) + aoff + m * 2048 + k * 1024); } while (0)
; #define PG8_MMA(ai, bj, At, Bt) do { __builtin_amdgcn_s_setprio(1); _Pragma("unroll") for (int m = 0; m < 4; ++m) _Pragma("unroll") for (int n = 0; n < 2; ++n) _Pragma("unroll") for (int k = 0; k < 2; ++k) \
;         acc[ai][bj][m][n] = __builtin_amdgcn_mfma_f32_16x16x32_bf16(Bt[n][k], At[m][k], acc[ai][bj][m][n], 0, 0, 0); __builtin_amdgcn_s_setprio(0); } while (0)
; #define PG8_WAIT_V(n) asm volatile("s_waitcnt vmcnt(" #n ")" ::: "memory")
; #define PG8_WAIT_L(n) asm volatile("s_waitcnt lgkmcnt(" #n ")" ::: "memory")
; #define PG8_BAR __builtin_amdgcn_s_barrier()
; #define PG8_SCHED __builtin_amdgcn_sched_barrier(0)
; template <class Epi>
; __device__ __forceinline__ void gemm_phase(LAS unsigned char* lds, const Gemm g, const StaticOrder& S, const Epi& E) {
;     ...
;             PG8_BAR; PG8_WAIT_L(0); PG8_MMA(0, 1, At, B1); PG8_BAR;
;             PG8_LDA(At, 1, 1); PG8_STAGE(PG8_SA(1, 0), a3, voffA);
;             PG8_BAR; PG8_WAIT_L(0); PG8_MMA(1, 0, At, B0); PG8_BAR; PG8_SCHED;
;             PG8_STAGE(PG8_SB(1, 1), b3 + hstep, voffB);
;             PG8_WAIT_V(6); PG8_BAR; PG8_MMA(1, 1, At, B1); PG8_BAR;
	s_waitcnt lgkmcnt(0)
	s_waitcnt lgkmcnt(0)
	v_mfma_f32_16x16x32_bf16 v[60:63], v[156:159], v[172:175], v[60:63]
	v_mfma_f32_16x16x32_bf16 v[56:59], v[164:167], v[172:175], v[56:59]
	v_mfma_f32_16x16x32_bf16 v[52:55], v[156:159], v[180:183], v[52:55]
	v_mfma_f32_16x16x32_bf16 v[48:51], v[164:167], v[180:183], v[48:51]
	v_mfma_f32_16x16x32_bf16 v[36:39], v[156:159], v[188:191], v[36:39]
	v_mfma_f32_16x16x32_bf16 v[32:35], v[164:167], v[188:191], v[32:35]
	v_mfma_f32_16x16x32_bf16 v[20:23], v[156:159], v[196:199], v[20:23]
	v_mfma_f32_16x16x32_bf16 v[16:19], v[164:167], v[196:199], v[16:19]
	v_mfma_f32_16x16x32_bf16 v[60:63], v[160:163], v[176:179], v[60:63]
	v_mfma_f32_16x16x32_bf16 v[56:59], v[168:171], v[176:179], v[56:59]
	v_mfma_f32_16x16x32_bf16 v[52:55], v[160:163], v[184:187], v[52:55]
	v_mfma_f32_16x16x32_bf16 v[48:51], v[168:171], v[184:187], v[48:51]
	v_mfma_f32_16x16x32_bf16 v[36:39], v[160:163], v[192:195], v[36:39]
	v_mfma_f32_16x16x32_bf16 v[32:35], v[168:171], v[192:195], v[32:35]
	v_mfma_f32_16x16x32_bf16 v[20:23], v[160:163], v[200:203], v[20:23]
	v_mfma_f32_16x16x32_bf16 v[16:19], v[168:171], v[200:203], v[16:19]
	s_barrier
	s_add_u32 s34, s34, 0x80080
	s_addc_u32 s35, s35, 0
	s_add_i32 s40, s40, s43
	s_mov_b32 m0, s40
	s_nop 0
	global_load_lds_dwordx4 v138, s[34:35]
	s_add_i32 m0, s40, 0x2000
	s_nop 0
	global_load_lds_dwordx4 v134, s[34:35]
	s_waitcnt vmcnt(6)
	s_barrier
	v_mfma_f32_16x16x32_bf16 v[44:47], v[204:207], v[172:175], v[44:47]
	v_mfma_f32_16x16x32_bf16 v[40:43], v[212:215], v[172:175], v[40:43]
	v_mfma_f32_16x16x32_bf16 v[28:31], v[204:207], v[180:183], v[28:31]
	v_mfma_f32_16x16x32_bf16 v[24:27], v[212:215], v[180:183], v[24:27]
	v_mfma_f32_16x16x32_bf16 v[12:15], v[204:207], v[188:191], v[12:15]
	v_mfma_f32_16x16x32_bf16 v[8:11], v[212:215], v[188:191], v[8:11]
	v_mfma_f32_16x16x32_bf16 v[4:7], v[204:207], v[196:199], v[4:7]
	v_mfma_f32_16x16x32_bf16 v[0:3], v[212:215], v[196:199], v[0:3]
	v_mfma_f32_16x16x32_bf16 v[44:47], v[208:211], v[176:179], v[44:47]
	v_mfma_f32_16x16x32_bf16 v[40:43], v[216:219], v[176:179], v[40:43]
	v_mfma_f32_16x16x32_bf16 v[28:31], v[208:211], v[184:187], v[28:31]
	v_mfma_f32_16x16x32_bf16 v[24:27], v[216:219], v[184:187], v[24:27]
	v_mfma_f32_16x16x32_bf16 v[12:15], v[208:211], v[192:195], v[12:15]
	v_mfma_f32_16x16x32_bf16 v[8:11], v[216:219], v[192:195], v[8:11]
	v_mfma_f32_16x16x32_bf16 v[4:7], v[208:211], v[200:203], v[4:7]
	v_mfma_f32_16x16x32_bf16 v[0:3], v[216:219], v[200:203], v[0:3]
	s_add_i32 s65, s65, 2
	s_add_u32 s30, s30, 0x100
	s_addc_u32 s31, s31, 0
	s_add_u32 s63, s63, 0x100
	s_addc_u32 s64, s64, 0
	s_cmp_gt_u32 s65, 29
	s_barrier
	s_cbranch_scc0 .LBB0_559
; __device__ __forceinline__ unsigned pk_bf16(float lo, float hi) { const f32x2 v = (f32x2){lo, hi}; const bf16v2 b = __builtin_convertvector(v, bf16v2); return __builtin_bit_cast(unsigned, b); }
; #define PG8_WAIT_V(n) asm volatile("s_waitcnt vmcnt(" #n ")" ::: "memory")
; #define PG8_BAR __builtin_amdgcn_s_barrier()
; template <class Epi>
; __device__ __forceinline__ void gemm_phase(LAS unsigned char* lds, const Gemm g, const StaticOrder& S, const Epi& E) {
;     ...
;         if (!has_next) break;
; #pragma unroll
;         for (int a = 0; a < 2; ++a)
; #pragma unroll
;             for (int b = 0; b < 2; ++b)
; #pragma unroll
;                 for (int m = 0; m < 4; ++m)
; #pragma unroll
;                     for (int n = 0; n < 2; ++n) acc[a][b][m][n] = (f32x4){0.f, 0.f, 0.f, 0.f};
;         cur = nxt; cA = nA; cB = nB; ++ui;
;     }
;     PG8_WAIT_V(0);
;     if (wr == 0) PG8_BAR;
;     __device__ __forceinline__ void operator()(const f32x4 (&acc)[2][2][4][2], const pg8::Unit& u, int wr, int wc, int fr, int fq) const {
;         const int row0 = u.pm * 256 + wr * 64 + fr, col0 = u.pn * 256 + wc * 32 + 8 * fq;
; #pragma unroll
;         for (int ai = 0; ai < 2; ++ai)
; #pragma unroll
;             for (int m = 0; m < 4; ++m) {
;                 const int row = row0 + ai * 128 + m * 16;
;                 bf16_t* orow = yb + (size_t)row * DM + col0;
; #pragma unroll
;                 for (int bj = 0; bj < 2; ++bj) {
;                     const f32x4 v0 = acc[ai][bj][m][0], v1 = acc[ai][bj][m][1];
;                     *(u32x4*)(orow + bj * 128) = (u32x4){pk_bf16(v0[0], v0[1]), pk_bf16(v0[2], v0[3]), pk_bf16(v1[0], v1[1]), pk_bf16(v1[2], v1[3])};
;                 }
;             }
	v_lshl_add_u32 v156, s20, 8, v150
	v_lshl_or_b32 v158, s60, 8, v152
	v_ashrrev_i32_e32 v157, 31, v156
	v_ashrrev_i32_e32 v159, 31, v158
	v_lshlrev_b64 v[160:161], 12, v[156:157]
	v_lshl_add_u64 v[160:161], s[6:7], 0, v[160:161]
	v_lshlrev_b64 v[158:159], 1, v[158:159]
	v_lshl_add_u64 v[160:161], v[160:161], 0, v[158:159]
	v_cvt_pk_bf16_f32 v60, v60, v61
	v_cvt_pk_bf16_f32 v61, v62, v63
	v_cvt_pk_bf16_f32 v62, v56, v57
	v_add_co_u32_e32 v56, vcc, s56, v160
	v_cvt_pk_bf16_f32 v68, v68, v69
	v_cvt_pk_bf16_f32 v69, v70, v71
	v_cvt_pk_bf16_f32 v70, v64, v65
	v_lshl_add_u64 v[64:65], v[160:161], 0, s[10:11]
	v_addc_co_u32_e32 v57, vcc, 0, v161, vcc
	v_cvt_pk_bf16_f32 v44, v44, v45
	v_cvt_pk_bf16_f32 v45, v46, v47
	v_cvt_pk_bf16_f32 v46, v40, v41
	v_cvt_pk_bf16_f32 v47, v42, v43
	v_cvt_pk_bf16_f32 v108, v108, v109
	v_cvt_pk_bf16_f32 v109, v110, v111
	v_cvt_pk_bf16_f32 v110, v104, v105
	v_or_b32_e32 v104, 16, v156
	global_store_dwordx4 v[64:65], v[44:47], off offset:256
	v_ashrrev_i32_e32 v105, 31, v104
	v_cvt_pk_bf16_f32 v92, v92, v93
	v_add_co_u32_e32 v46, vcc, s57, v160
	v_cvt_pk_bf16_f32 v93, v94, v95
	v_cvt_pk_bf16_f32 v94, v88, v89
	v_or_b32_e32 v88, 32, v156
	v_lshl_add_u64 v[44:45], v[160:161], 0, s[14:15]
	v_addc_co_u32_e32 v47, vcc, 0, v161, vcc
	v_cvt_pk_bf16_f32 v28, v28, v29
	v_cvt_pk_bf16_f32 v29, v30, v31
	v_cvt_pk_bf16_f32 v30, v24, v25
	v_cvt_pk_bf16_f32 v31, v26, v27
	v_lshlrev_b64 v[104:105], 12, v[104:105]
	v_ashrrev_i32_e32 v89, 31, v88
	v_cvt_pk_bf16_f32 v76, v76, v77
	v_cvt_pk_bf16_f32 v77, v78, v79
	v_cvt_pk_bf16_f32 v78, v72, v73
	v_or_b32_e32 v72, 48, v156
	global_store_dwordx4 v[44:45], v[28:31], off offset:256
	v_cvt_pk_bf16_f32 v111, v106, v107
	v_lshl_add_u64 v[104:105], s[6:7], 0, v[104:105]
	v_add_co_u32_e32 v30, vcc, s58, v160
	v_lshlrev_b64 v[88:89], 12, v[88:89]
	v_ashrrev_i32_e32 v73, 31, v72
	v_lshl_add_u64 v[28:29], v[160:161], 0, s[16:17]
	v_addc_co_u32_e32 v31, vcc, 0, v161, vcc
	v_cvt_pk_bf16_f32 v12, v12, v13
	v_cvt_pk_bf16_f32 v13, v14, v15
	v_cvt_pk_bf16_f32 v14, v8, v9
	v_cvt_pk_bf16_f32 v15, v10, v11
	global_store_dwordx4 v[160:161], v[108:111], off offset:256
	v_cvt_pk_bf16_f32 v95, v90, v91
	v_lshl_add_u64 v[88:89], s[6:7], 0, v[88:89]
	v_lshl_add_u64 v[108:109], v[104:105], 0, v[158:159]
	v_lshlrev_b64 v[72:73], 12, v[72:73]
	global_store_dwordx4 v[28:29], v[12:15], off offset:256
	global_store_dwordx4 v[108:109], v[92:95], off offset:256
	v_cvt_pk_bf16_f32 v79, v74, v75
	v_add_co_u32_e32 v14, vcc, s59, v160
	v_lshl_add_u64 v[92:93], v[88:89], 0, v[158:159]
	v_lshl_add_u64 v[72:73], s[6:7], 0, v[72:73]
	v_addc_co_u32_e32 v15, vcc, 0, v161, vcc
	v_cvt_pk_bf16_f32 v124, v124, v125
	v_cvt_pk_bf16_f32 v125, v126, v127
	v_cvt_pk_bf16_f32 v126, v120, v121
	v_cvt_pk_bf16_f32 v127, v122, v123
	v_cvt_pk_bf16_f32 v104, v116, v117
	v_cvt_pk_bf16_f32 v105, v118, v119
	v_cvt_pk_bf16_f32 v106, v112, v113
	v_cvt_pk_bf16_f32 v107, v114, v115
	v_cvt_pk_bf16_f32 v88, v100, v101
	v_cvt_pk_bf16_f32 v89, v102, v103
	v_cvt_pk_bf16_f32 v90, v96, v97
	v_cvt_pk_bf16_f32 v91, v98, v99
	global_store_dwordx4 v[92:93], v[76:79], off offset:256
	v_cvt_pk_bf16_f32 v74, v80, v81
	v_cvt_pk_bf16_f32 v75, v82, v83
	v_lshl_add_u64 v[76:77], v[72:73], 0, v[158:159]
	v_cvt_pk_bf16_f32 v72, v84, v85
	v_cvt_pk_bf16_f32 v73, v86, v87
	v_cvt_pk_bf16_f32 v71, v66, v67
	v_cvt_pk_bf16_f32 v63, v58, v59
	v_cvt_pk_bf16_f32 v40, v52, v53
	v_cvt_pk_bf16_f32 v41, v54, v55
	v_cvt_pk_bf16_f32 v42, v48, v49
	v_cvt_pk_bf16_f32 v43, v50, v51
	v_cvt_pk_bf16_f32 v24, v36, v37
	v_cvt_pk_bf16_f32 v25, v38, v39
	v_cvt_pk_bf16_f32 v26, v32, v33
	v_cvt_pk_bf16_f32 v27, v34, v35
	v_lshl_add_u64 v[12:13], v[160:161], 0, s[18:19]
	v_cvt_pk_bf16_f32 v8, v20, v21
	v_cvt_pk_bf16_f32 v9, v22, v23
	v_cvt_pk_bf16_f32 v10, v16, v17
	v_cvt_pk_bf16_f32 v11, v18, v19
	v_cvt_pk_bf16_f32 v4, v4, v5
	v_cvt_pk_bf16_f32 v5, v6, v7
	v_cvt_pk_bf16_f32 v6, v0, v1
	v_cvt_pk_bf16_f32 v7, v2, v3
	s_and_b64 vcc, exec, s[8:9]
	s_mov_b32 s60, s22
	s_mov_b32 s20, s24
	s_mov_b64 s[34:35], s[28:29]
	s_mov_b64 s[30:31], s[26:27]
	s_mov_b32 s40, s70
	global_store_dwordx4 v[160:161], v[124:127], off
	global_store_dwordx4 v[108:109], v[104:107], off
	global_store_dwordx4 v[92:93], v[88:91], off
	global_store_dwordx4 v[76:77], v[72:75], off
	global_store_dwordx4 v[76:77], v[68:71], off offset:256
	global_store_dwordx4 v[56:57], v[60:63], off
	global_store_dwordx4 v[46:47], v[40:43], off
	global_store_dwordx4 v[30:31], v[24:27], off
	global_store_dwordx4 v[14:15], v[8:11], off
	global_store_dwordx4 v[12:13], v[4:7], off offset:256
	s_cbranch_vccnz .Lg2_exit
	s_cmp_lg_u32 s49, 4
	s_cbranch_scc1 .LBB0_556
	s_waitcnt vmcnt(0)
	s_barrier
	s_lshr_b32 s8, s42, 6
	s_cmp_lg_u32 s8, 4
	s_cbranch_scc1 .LBB0_556
	buffer_wbl2 sc1
	s_waitcnt vmcnt(0)
	s_mov_b64 s[8:9], exec
	s_mov_b64 exec, 1
	v_mov_b32_e32 v0, 0
	v_mov_b32_e32 v1, 1
	global_atomic_add v0, v1, s[36:37] offset:256
	s_mov_b64 exec, s[8:9]
	s_branch .LBB0_556
